# K-tile prefetch for next unit, end-of-unit ticket wait relaxed to vmcnt(20) so wave 0 does not wait for the prefetch
# speedup vs baseline: 1.0104x; 1.0033x over previous
.LBB0_517:
	s_or_b64 exec, exec, s[0:1]
	v_readlane_b32 s0, v250, 36
	v_readlane_b32 s1, v250, 37
	s_and_b64 s[36:37], s[0:1], s[44:45]
	s_and_saveexec_b64 s[0:1], s[36:37]
	s_cbranch_execz .LBB0_407
	s_cmp_lg_u32 s86, -1
	s_cselect_b32 s36, s86, 0
	s_cselect_b32 s37, s5, 0
	v_mov_b32_e32 v0, s36
	v_mov_b32_e32 v1, s37
	s_waitcnt vmcnt(20)
	ds_write_b32 v0, v196
	s_waitcnt lgkmcnt(0)
	s_branch .LBB0_407
